# P5 and P7 GEMM epilogues: all residual loads issued up front (16 serialized load-wait-store steps per tile removed)
# speedup vs baseline: 1.0115x; 1.0029x over previous
.LBB0_796:
	s_and_saveexec_b64 s[10:11], s[4:5]
	ds_write_b32 v153, v131
	s_or_b64 exec, exec, s[10:11]
	s_lshl_b32 s42, s42, 8
	v_add_u32_e32 v148, s42, v150
	v_ashrrev_i32_e32 v149, 31, v148
	v_lshl_or_b32 v146, s40, 8, v152
	v_lshlrev_b64 v[160:161], 12, v[148:149]
	v_ashrrev_i32_e32 v147, 31, v146
	v_lshl_add_u64 v[160:161], s[66:67], 0, v[160:161]
	v_lshl_add_u64 v[168:169], v[146:147], 1, v[160:161]
	v_lshl_add_u32 v144, v148, 11, v146
	v_lshlrev_b32_e32 v144, 1, v144
	global_load_dwordx4 v[178:181], v144, s[66:67]
	global_load_dwordx4 v[182:185], v144, s[66:67] offset:256
	v_add_u32_e32 v145, 0x10000, v144
	global_load_dwordx4 v[186:189], v145, s[66:67]
	global_load_dwordx4 v[190:193], v145, s[66:67] offset:256
	v_add_u32_e32 v145, 0x20000, v144
	global_load_dwordx4 v[194:197], v145, s[66:67]
	global_load_dwordx4 v[198:201], v145, s[66:67] offset:256
	v_add_u32_e32 v145, 0x30000, v144
	global_load_dwordx4 v[202:205], v145, s[66:67]
	global_load_dwordx4 v[214:217], v145, s[66:67] offset:256
	v_add_u32_e32 v145, 0x80000, v144
	global_load_dwordx4 v[218:221], v145, s[66:67]
	global_load_dwordx4 v[222:225], v145, s[66:67] offset:256
	v_add_u32_e32 v145, 0x90000, v144
	global_load_dwordx4 v[226:229], v145, s[66:67]
	global_load_dwordx4 v[230:233], v145, s[66:67] offset:256
	v_add_u32_e32 v145, 0xa0000, v144
	global_load_dwordx4 v[234:237], v145, s[66:67]
	global_load_dwordx4 v[238:241], v145, s[66:67] offset:256
	v_add_u32_e32 v145, 0xb0000, v144
	global_load_dwordx4 v[242:245], v145, s[66:67]
	global_load_dwordx4 v[248:251], v145, s[66:67] offset:256
	s_waitcnt lgkmcnt(0)
	s_barrier
	s_waitcnt vmcnt(14)
	v_mov_b32_e32 v160, v178
	v_mov_b32_e32 v161, v179
	v_mov_b32_e32 v162, v180
	v_mov_b32_e32 v163, v181
	v_mov_b32_e32 v164, v182
	v_mov_b32_e32 v165, v183
	v_mov_b32_e32 v166, v184
	v_mov_b32_e32 v167, v185
	v_lshlrev_b32_e32 v170, 16, v160
	v_and_b32_e32 v171, 0xffff0000, v160
	v_lshlrev_b32_e32 v174, 16, v164
	v_and_b32_e32 v175, 0xffff0000, v164
	v_lshlrev_b32_e32 v160, 16, v161
	v_and_b32_e32 v161, 0xffff0000, v161
	v_lshlrev_b32_e32 v176, 16, v166
	v_and_b32_e32 v177, 0xffff0000, v166
	v_lshlrev_b32_e32 v166, 16, v167
	v_and_b32_e32 v167, 0xffff0000, v167
	v_pk_add_f32 v[124:125], v[124:125], v[170:171]
	v_pk_add_f32 v[116:117], v[116:117], v[174:175]
	v_lshlrev_b32_e32 v164, 16, v165
	v_and_b32_e32 v165, 0xffff0000, v165
	v_pk_add_f32 v[126:127], v[126:127], v[160:161]
	v_pk_add_f32 v[160:161], v[114:115], v[166:167]
	v_mul_f32_e32 v114, v125, v125
	v_mul_f32_e32 v115, v117, v117
	v_pk_add_f32 v[118:119], v[118:119], v[164:165]
	v_fmac_f32_e32 v114, v124, v124
	v_fmac_f32_e32 v115, v116, v116
	v_lshlrev_b32_e32 v172, 16, v162
	v_and_b32_e32 v173, 0xffff0000, v162
	v_lshlrev_b32_e32 v162, 16, v163
	v_and_b32_e32 v163, 0xffff0000, v163
	v_fmac_f32_e32 v114, v126, v126
	v_fmac_f32_e32 v115, v118, v118
	v_pk_add_f32 v[122:123], v[122:123], v[162:163]
	v_pk_add_f32 v[120:121], v[120:121], v[172:173]
	v_pk_add_f32 v[162:163], v[112:113], v[176:177]
	v_fmac_f32_e32 v114, v127, v127
	v_fmac_f32_e32 v115, v119, v119
	v_fmac_f32_e32 v114, v120, v120
	v_fmac_f32_e32 v115, v162, v162
	v_fmac_f32_e32 v114, v121, v121
	v_fmac_f32_e32 v115, v163, v163
	v_fmac_f32_e32 v114, v122, v122
	v_fmac_f32_e32 v115, v160, v160
	v_fmac_f32_e32 v114, v123, v123
	v_fmac_f32_e32 v115, v161, v161
	v_cvt_pk_bf16_f32 v112, v124, v125
	v_add_f32_e32 v124, v114, v115
	ds_bpermute_b32 v125, v211, v124
	v_cvt_pk_bf16_f32 v113, v126, v127
	v_cvt_pk_bf16_f32 v114, v120, v121
	v_cvt_pk_bf16_f32 v115, v122, v123
	global_store_dwordx4 v[168:169], v[112:115], off
	s_waitcnt lgkmcnt(0)
	s_nop 0
	v_add_f32_e32 v112, v124, v125
	ds_bpermute_b32 v113, v212, v112
	v_cvt_pk_bf16_f32 v114, v116, v117
	v_cvt_pk_bf16_f32 v115, v118, v119
	v_cvt_pk_bf16_f32 v116, v162, v163
	v_cvt_pk_bf16_f32 v117, v160, v161
	global_store_dwordx4 v[168:169], v[114:117], off offset:256
	s_and_saveexec_b64 s[10:11], s[6:7]
	s_cbranch_execz .LBB0_800
	s_waitcnt lgkmcnt(0)
	v_add_f32_e32 v112, v112, v113
	ds_add_f32 v154, v112
.LBB0_800:
	s_or_b64 exec, exec, s[10:11]
	v_or_b32_e32 v112, 16, v148
	s_waitcnt lgkmcnt(0)
	v_ashrrev_i32_e32 v113, 31, v112
	v_lshlrev_b64 v[112:113], 12, v[112:113]
	v_lshl_add_u64 v[112:113], s[66:67], 0, v[112:113]
	v_lshl_add_u64 v[120:121], v[146:147], 1, v[112:113]
	s_waitcnt vmcnt(14)
	v_mov_b32_e32 v112, v186
	v_mov_b32_e32 v113, v187
	v_mov_b32_e32 v114, v188
	v_mov_b32_e32 v115, v189
	v_mov_b32_e32 v116, v190
	v_mov_b32_e32 v117, v191
	v_mov_b32_e32 v118, v192
	v_mov_b32_e32 v119, v193
	v_lshlrev_b32_e32 v122, 16, v112
	v_and_b32_e32 v123, 0xffff0000, v112
	v_lshlrev_b32_e32 v126, 16, v116
	v_and_b32_e32 v127, 0xffff0000, v116
	v_lshlrev_b32_e32 v112, 16, v113
	v_and_b32_e32 v113, 0xffff0000, v113
	v_lshlrev_b32_e32 v160, 16, v118
	v_and_b32_e32 v161, 0xffff0000, v118
	v_lshlrev_b32_e32 v118, 16, v119
	v_and_b32_e32 v119, 0xffff0000, v119
	v_pk_add_f32 v[108:109], v[108:109], v[122:123]
	v_pk_add_f32 v[100:101], v[100:101], v[126:127]
	v_lshlrev_b32_e32 v116, 16, v117
	v_and_b32_e32 v117, 0xffff0000, v117
	v_pk_add_f32 v[110:111], v[110:111], v[112:113]
	v_pk_add_f32 v[112:113], v[98:99], v[118:119]
	v_mul_f32_e32 v98, v109, v109
	v_mul_f32_e32 v99, v101, v101
	v_pk_add_f32 v[102:103], v[102:103], v[116:117]
	v_fmac_f32_e32 v98, v108, v108
	v_fmac_f32_e32 v99, v100, v100
	v_lshlrev_b32_e32 v124, 16, v114
	v_and_b32_e32 v125, 0xffff0000, v114
	v_lshlrev_b32_e32 v114, 16, v115
	v_and_b32_e32 v115, 0xffff0000, v115
	v_fmac_f32_e32 v98, v110, v110
	v_fmac_f32_e32 v99, v102, v102
	v_pk_add_f32 v[106:107], v[106:107], v[114:115]
	v_pk_add_f32 v[104:105], v[104:105], v[124:125]
	v_pk_add_f32 v[114:115], v[96:97], v[160:161]
	v_fmac_f32_e32 v98, v111, v111
	v_fmac_f32_e32 v99, v103, v103
	v_fmac_f32_e32 v98, v104, v104
	v_fmac_f32_e32 v99, v114, v114
	v_fmac_f32_e32 v98, v105, v105
	v_fmac_f32_e32 v99, v115, v115
	v_fmac_f32_e32 v98, v106, v106
	v_fmac_f32_e32 v99, v112, v112
	v_fmac_f32_e32 v98, v107, v107
	v_fmac_f32_e32 v99, v113, v113
	v_cvt_pk_bf16_f32 v96, v108, v109
	v_add_f32_e32 v108, v98, v99
	ds_bpermute_b32 v109, v211, v108
	v_cvt_pk_bf16_f32 v97, v110, v111
	v_cvt_pk_bf16_f32 v98, v104, v105
	v_cvt_pk_bf16_f32 v99, v106, v107
	global_store_dwordx4 v[120:121], v[96:99], off
	s_waitcnt lgkmcnt(0)
	s_nop 0
	v_add_f32_e32 v96, v108, v109
	ds_bpermute_b32 v97, v212, v96
	v_cvt_pk_bf16_f32 v98, v100, v101
	v_cvt_pk_bf16_f32 v99, v102, v103
	v_cvt_pk_bf16_f32 v100, v114, v115
	v_cvt_pk_bf16_f32 v101, v112, v113
	global_store_dwordx4 v[120:121], v[98:101], off offset:256
	s_and_saveexec_b64 s[10:11], s[6:7]
	s_cbranch_execz .LBB0_802
	s_waitcnt lgkmcnt(0)
	v_add_f32_e32 v96, v96, v97
	ds_add_f32 v154, v96 offset:64
.LBB0_802:
	s_or_b64 exec, exec, s[10:11]
	v_or_b32_e32 v96, 32, v148
	s_waitcnt lgkmcnt(0)
	v_ashrrev_i32_e32 v97, 31, v96
	v_lshlrev_b64 v[96:97], 12, v[96:97]
	v_lshl_add_u64 v[96:97], s[66:67], 0, v[96:97]
	v_lshl_add_u64 v[104:105], v[146:147], 1, v[96:97]
	s_waitcnt vmcnt(14)
	v_mov_b32_e32 v96, v194
	v_mov_b32_e32 v97, v195
	v_mov_b32_e32 v98, v196
	v_mov_b32_e32 v99, v197
	v_mov_b32_e32 v100, v198
	v_mov_b32_e32 v101, v199
	v_mov_b32_e32 v102, v200
	v_mov_b32_e32 v103, v201
	v_lshlrev_b32_e32 v106, 16, v96
	v_and_b32_e32 v107, 0xffff0000, v96
	v_lshlrev_b32_e32 v110, 16, v100
	v_and_b32_e32 v111, 0xffff0000, v100
	v_lshlrev_b32_e32 v96, 16, v97
	v_and_b32_e32 v97, 0xffff0000, v97
	v_lshlrev_b32_e32 v112, 16, v102
	v_and_b32_e32 v113, 0xffff0000, v102
	v_lshlrev_b32_e32 v102, 16, v103
	v_and_b32_e32 v103, 0xffff0000, v103
	v_pk_add_f32 v[92:93], v[92:93], v[106:107]
	v_pk_add_f32 v[84:85], v[84:85], v[110:111]
	v_lshlrev_b32_e32 v100, 16, v101
	v_and_b32_e32 v101, 0xffff0000, v101
	v_pk_add_f32 v[94:95], v[94:95], v[96:97]
	v_pk_add_f32 v[96:97], v[82:83], v[102:103]
	v_mul_f32_e32 v82, v93, v93
	v_mul_f32_e32 v83, v85, v85
	v_pk_add_f32 v[86:87], v[86:87], v[100:101]
	v_fmac_f32_e32 v82, v92, v92
	v_fmac_f32_e32 v83, v84, v84
	v_lshlrev_b32_e32 v108, 16, v98
	v_and_b32_e32 v109, 0xffff0000, v98
	v_lshlrev_b32_e32 v98, 16, v99
	v_and_b32_e32 v99, 0xffff0000, v99
	v_fmac_f32_e32 v82, v94, v94
	v_fmac_f32_e32 v83, v86, v86
	v_pk_add_f32 v[90:91], v[90:91], v[98:99]
	v_pk_add_f32 v[88:89], v[88:89], v[108:109]
	v_pk_add_f32 v[98:99], v[80:81], v[112:113]
	v_fmac_f32_e32 v82, v95, v95
	v_fmac_f32_e32 v83, v87, v87
	v_fmac_f32_e32 v82, v88, v88
	v_fmac_f32_e32 v83, v98, v98
	v_fmac_f32_e32 v82, v89, v89
	v_fmac_f32_e32 v83, v99, v99
	v_fmac_f32_e32 v82, v90, v90
	v_fmac_f32_e32 v83, v96, v96
	v_fmac_f32_e32 v82, v91, v91
	v_fmac_f32_e32 v83, v97, v97
	v_cvt_pk_bf16_f32 v80, v92, v93
	v_add_f32_e32 v92, v82, v83
	ds_bpermute_b32 v93, v211, v92
	v_cvt_pk_bf16_f32 v81, v94, v95
	v_cvt_pk_bf16_f32 v82, v88, v89
	v_cvt_pk_bf16_f32 v83, v90, v91
	global_store_dwordx4 v[104:105], v[80:83], off
	s_waitcnt lgkmcnt(0)
	s_nop 0
	v_add_f32_e32 v80, v92, v93
	ds_bpermute_b32 v81, v212, v80
	v_cvt_pk_bf16_f32 v82, v84, v85
	v_cvt_pk_bf16_f32 v83, v86, v87
	v_cvt_pk_bf16_f32 v84, v98, v99
	v_cvt_pk_bf16_f32 v85, v96, v97
	global_store_dwordx4 v[104:105], v[82:85], off offset:256
	s_and_saveexec_b64 s[10:11], s[6:7]
	s_cbranch_execz .LBB0_804
	s_waitcnt lgkmcnt(0)
	v_add_f32_e32 v80, v80, v81
	ds_add_f32 v154, v80 offset:128
.LBB0_804:
	s_or_b64 exec, exec, s[10:11]
	v_or_b32_e32 v80, 48, v148
	s_waitcnt lgkmcnt(0)
	v_ashrrev_i32_e32 v81, 31, v80
	v_lshlrev_b64 v[80:81], 12, v[80:81]
	v_lshl_add_u64 v[80:81], s[66:67], 0, v[80:81]
	v_lshl_add_u64 v[88:89], v[146:147], 1, v[80:81]
	s_waitcnt vmcnt(14)
	v_mov_b32_e32 v80, v202
	v_mov_b32_e32 v81, v203
	v_mov_b32_e32 v82, v204
	v_mov_b32_e32 v83, v205
	v_mov_b32_e32 v84, v214
	v_mov_b32_e32 v85, v215
	v_mov_b32_e32 v86, v216
	v_mov_b32_e32 v87, v217
	v_lshlrev_b32_e32 v90, 16, v80
	v_and_b32_e32 v91, 0xffff0000, v80
	v_lshlrev_b32_e32 v94, 16, v84
	v_and_b32_e32 v95, 0xffff0000, v84
	v_lshlrev_b32_e32 v80, 16, v81
	v_and_b32_e32 v81, 0xffff0000, v81
	v_lshlrev_b32_e32 v96, 16, v86
	v_and_b32_e32 v97, 0xffff0000, v86
	v_lshlrev_b32_e32 v86, 16, v87
	v_and_b32_e32 v87, 0xffff0000, v87
	v_pk_add_f32 v[76:77], v[76:77], v[90:91]
	v_pk_add_f32 v[68:69], v[68:69], v[94:95]
	v_lshlrev_b32_e32 v84, 16, v85
	v_and_b32_e32 v85, 0xffff0000, v85
	v_pk_add_f32 v[78:79], v[78:79], v[80:81]
	v_pk_add_f32 v[80:81], v[66:67], v[86:87]
	v_mul_f32_e32 v66, v77, v77
	v_mul_f32_e32 v67, v69, v69
	v_pk_add_f32 v[70:71], v[70:71], v[84:85]
	v_fmac_f32_e32 v66, v76, v76
	v_fmac_f32_e32 v67, v68, v68
	v_lshlrev_b32_e32 v92, 16, v82
	v_and_b32_e32 v93, 0xffff0000, v82
	v_lshlrev_b32_e32 v82, 16, v83
	v_and_b32_e32 v83, 0xffff0000, v83
	v_fmac_f32_e32 v66, v78, v78
	v_fmac_f32_e32 v67, v70, v70
	v_pk_add_f32 v[74:75], v[74:75], v[82:83]
	v_pk_add_f32 v[72:73], v[72:73], v[92:93]
	v_pk_add_f32 v[82:83], v[64:65], v[96:97]
	v_fmac_f32_e32 v66, v79, v79
	v_fmac_f32_e32 v67, v71, v71
	v_fmac_f32_e32 v66, v72, v72
	v_fmac_f32_e32 v67, v82, v82
	v_fmac_f32_e32 v66, v73, v73
	v_fmac_f32_e32 v67, v83, v83
	v_fmac_f32_e32 v66, v74, v74
	v_fmac_f32_e32 v67, v80, v80
	v_fmac_f32_e32 v66, v75, v75
	v_fmac_f32_e32 v67, v81, v81
	v_cvt_pk_bf16_f32 v64, v76, v77
	v_add_f32_e32 v76, v66, v67
	ds_bpermute_b32 v77, v211, v76
	v_cvt_pk_bf16_f32 v65, v78, v79
	v_cvt_pk_bf16_f32 v66, v72, v73
	v_cvt_pk_bf16_f32 v67, v74, v75
	global_store_dwordx4 v[88:89], v[64:67], off
	s_waitcnt lgkmcnt(0)
	s_nop 0
	v_add_f32_e32 v64, v76, v77
	ds_bpermute_b32 v65, v212, v64
	v_cvt_pk_bf16_f32 v66, v68, v69
	v_cvt_pk_bf16_f32 v67, v70, v71
	v_cvt_pk_bf16_f32 v68, v82, v83
	v_cvt_pk_bf16_f32 v69, v80, v81
	global_store_dwordx4 v[88:89], v[66:69], off offset:256
	s_and_saveexec_b64 s[10:11], s[6:7]
	s_cbranch_execz .LBB0_806
	s_waitcnt lgkmcnt(0)
	v_add_f32_e32 v64, v64, v65
	ds_add_f32 v154, v64 offset:192
.LBB0_806:
	s_or_b64 exec, exec, s[10:11]
	s_waitcnt lgkmcnt(0)
	v_lshlrev_b64 v[64:65], 12, v[148:149]
	v_lshl_add_u64 v[64:65], s[66:67], 0, v[64:65]
	v_lshl_add_u64 v[64:65], v[146:147], 1, v[64:65]
	v_add_co_u32_e32 v74, vcc, 0x80000, v64
	v_lshl_add_u64 v[76:77], v[64:65], 0, s[0:1]
	s_nop 0
	v_addc_co_u32_e32 v75, vcc, 0, v65, vcc
	s_waitcnt vmcnt(14)
	v_mov_b32_e32 v66, v218
	v_mov_b32_e32 v67, v219
	v_mov_b32_e32 v68, v220
	v_mov_b32_e32 v69, v221
	v_mov_b32_e32 v70, v222
	v_mov_b32_e32 v71, v223
	v_mov_b32_e32 v72, v224
	v_mov_b32_e32 v73, v225
	v_lshlrev_b32_e32 v78, 16, v66
	v_and_b32_e32 v79, 0xffff0000, v66
	v_lshlrev_b32_e32 v82, 16, v70
	v_and_b32_e32 v83, 0xffff0000, v70
	v_lshlrev_b32_e32 v66, 16, v67
	v_and_b32_e32 v67, 0xffff0000, v67
	v_lshlrev_b32_e32 v84, 16, v72
	v_and_b32_e32 v85, 0xffff0000, v72
	v_lshlrev_b32_e32 v72, 16, v73
	v_and_b32_e32 v73, 0xffff0000, v73
	v_pk_add_f32 v[60:61], v[60:61], v[78:79]
	v_pk_add_f32 v[52:53], v[52:53], v[82:83]
	v_lshlrev_b32_e32 v70, 16, v71
	v_and_b32_e32 v71, 0xffff0000, v71
	v_pk_add_f32 v[62:63], v[62:63], v[66:67]
	v_pk_add_f32 v[66:67], v[50:51], v[72:73]
	v_mul_f32_e32 v50, v61, v61
	v_mul_f32_e32 v51, v53, v53
	v_pk_add_f32 v[54:55], v[54:55], v[70:71]
	v_fmac_f32_e32 v50, v60, v60
	v_fmac_f32_e32 v51, v52, v52
	v_lshlrev_b32_e32 v80, 16, v68
	v_and_b32_e32 v81, 0xffff0000, v68
	v_lshlrev_b32_e32 v68, 16, v69
	v_and_b32_e32 v69, 0xffff0000, v69
	v_fmac_f32_e32 v50, v62, v62
	v_fmac_f32_e32 v51, v54, v54
	v_pk_add_f32 v[58:59], v[58:59], v[68:69]
	v_pk_add_f32 v[56:57], v[56:57], v[80:81]
	v_pk_add_f32 v[68:69], v[48:49], v[84:85]
	v_fmac_f32_e32 v50, v63, v63
	v_fmac_f32_e32 v51, v55, v55
	v_fmac_f32_e32 v50, v56, v56
	v_fmac_f32_e32 v51, v68, v68
	v_fmac_f32_e32 v50, v57, v57
	v_fmac_f32_e32 v51, v69, v69
	v_fmac_f32_e32 v50, v58, v58
	v_fmac_f32_e32 v51, v66, v66
	v_fmac_f32_e32 v50, v59, v59
	v_fmac_f32_e32 v51, v67, v67
	v_cvt_pk_bf16_f32 v48, v60, v61
	v_add_f32_e32 v60, v50, v51
	ds_bpermute_b32 v61, v211, v60
	v_cvt_pk_bf16_f32 v49, v62, v63
	v_cvt_pk_bf16_f32 v50, v56, v57
	v_cvt_pk_bf16_f32 v51, v58, v59
	global_store_dwordx4 v[74:75], v[48:51], off
	s_waitcnt lgkmcnt(0)
	s_nop 0
	v_add_f32_e32 v48, v60, v61
	ds_bpermute_b32 v49, v212, v48
	v_cvt_pk_bf16_f32 v50, v52, v53
	v_cvt_pk_bf16_f32 v51, v54, v55
	v_cvt_pk_bf16_f32 v52, v68, v69
	v_cvt_pk_bf16_f32 v53, v66, v67
	global_store_dwordx4 v[76:77], v[50:53], off offset:256
	s_and_saveexec_b64 s[10:11], s[6:7]
	s_cbranch_execz .LBB0_808
	s_waitcnt lgkmcnt(0)
	v_add_f32_e32 v48, v48, v49
	ds_add_f32 v155, v48
.LBB0_808:
	s_or_b64 exec, exec, s[10:11]
	v_add_co_u32_e32 v56, vcc, 0x90000, v64
	v_lshl_add_u64 v[58:59], v[64:65], 0, s[18:19]
	s_nop 0
	v_addc_co_u32_e32 v57, vcc, 0, v65, vcc
	s_waitcnt lgkmcnt(0)
	s_waitcnt vmcnt(14)
	v_mov_b32_e32 v48, v226
	v_mov_b32_e32 v49, v227
	v_mov_b32_e32 v50, v228
	v_mov_b32_e32 v51, v229
	v_mov_b32_e32 v52, v230
	v_mov_b32_e32 v53, v231
	v_mov_b32_e32 v54, v232
	v_mov_b32_e32 v55, v233
	v_lshlrev_b32_e32 v60, 16, v48
	v_and_b32_e32 v61, 0xffff0000, v48
	v_lshlrev_b32_e32 v64, 16, v52
	v_and_b32_e32 v65, 0xffff0000, v52
	v_lshlrev_b32_e32 v48, 16, v49
	v_and_b32_e32 v49, 0xffff0000, v49
	v_lshlrev_b32_e32 v66, 16, v54
	v_and_b32_e32 v67, 0xffff0000, v54
	v_lshlrev_b32_e32 v54, 16, v55
	v_and_b32_e32 v55, 0xffff0000, v55
	v_pk_add_f32 v[44:45], v[44:45], v[60:61]
	v_pk_add_f32 v[36:37], v[36:37], v[64:65]
	v_lshlrev_b32_e32 v52, 16, v53
	v_and_b32_e32 v53, 0xffff0000, v53
	v_pk_add_f32 v[46:47], v[46:47], v[48:49]
	v_pk_add_f32 v[48:49], v[34:35], v[54:55]
	v_mul_f32_e32 v34, v45, v45
	v_mul_f32_e32 v35, v37, v37
	v_pk_add_f32 v[38:39], v[38:39], v[52:53]
	v_fmac_f32_e32 v34, v44, v44
	v_fmac_f32_e32 v35, v36, v36
	v_lshlrev_b32_e32 v62, 16, v50
	v_and_b32_e32 v63, 0xffff0000, v50
	v_lshlrev_b32_e32 v50, 16, v51
	v_and_b32_e32 v51, 0xffff0000, v51
	v_fmac_f32_e32 v34, v46, v46
	v_fmac_f32_e32 v35, v38, v38
	v_pk_add_f32 v[42:43], v[42:43], v[50:51]
	v_pk_add_f32 v[40:41], v[40:41], v[62:63]
	v_pk_add_f32 v[50:51], v[32:33], v[66:67]
	v_fmac_f32_e32 v34, v47, v47
	v_fmac_f32_e32 v35, v39, v39
	v_fmac_f32_e32 v34, v40, v40
	v_fmac_f32_e32 v35, v50, v50
	v_fmac_f32_e32 v34, v41, v41
	v_fmac_f32_e32 v35, v51, v51
	v_fmac_f32_e32 v34, v42, v42
	v_fmac_f32_e32 v35, v48, v48
	v_fmac_f32_e32 v34, v43, v43
	v_fmac_f32_e32 v35, v49, v49
	v_cvt_pk_bf16_f32 v32, v44, v45
	v_add_f32_e32 v44, v34, v35
	ds_bpermute_b32 v45, v211, v44
	v_cvt_pk_bf16_f32 v33, v46, v47
	v_cvt_pk_bf16_f32 v34, v40, v41
	v_cvt_pk_bf16_f32 v35, v42, v43
	global_store_dwordx4 v[56:57], v[32:35], off
	s_waitcnt lgkmcnt(0)
	s_nop 0
	v_add_f32_e32 v32, v44, v45
	ds_bpermute_b32 v33, v212, v32
	v_cvt_pk_bf16_f32 v34, v36, v37
	v_cvt_pk_bf16_f32 v35, v38, v39
	v_cvt_pk_bf16_f32 v36, v50, v51
	v_cvt_pk_bf16_f32 v37, v48, v49
	global_store_dwordx4 v[58:59], v[34:37], off offset:256
	s_and_saveexec_b64 s[10:11], s[6:7]
	s_cbranch_execz .LBB0_810
	s_waitcnt lgkmcnt(0)
	v_add_f32_e32 v32, v32, v33
	ds_add_f32 v154, v32 offset:576
.LBB0_810:
	s_or_b64 exec, exec, s[10:11]
	s_waitcnt lgkmcnt(0)
	v_lshlrev_b64 v[32:33], 12, v[148:149]
	v_lshl_add_u64 v[32:33], s[66:67], 0, v[32:33]
	v_lshl_add_u64 v[32:33], v[146:147], 1, v[32:33]
	v_add_co_u32_e32 v42, vcc, 0xa0000, v32
	v_lshl_add_u64 v[44:45], v[32:33], 0, s[22:23]
	s_nop 0
	v_addc_co_u32_e32 v43, vcc, 0, v33, vcc
	s_waitcnt vmcnt(14)
	v_mov_b32_e32 v34, v234
	v_mov_b32_e32 v35, v235
	v_mov_b32_e32 v36, v236
	v_mov_b32_e32 v37, v237
	v_mov_b32_e32 v38, v238
	v_mov_b32_e32 v39, v239
	v_mov_b32_e32 v40, v240
	v_mov_b32_e32 v41, v241
	v_lshlrev_b32_e32 v46, 16, v34
	v_and_b32_e32 v47, 0xffff0000, v34
	v_lshlrev_b32_e32 v50, 16, v38
	v_and_b32_e32 v51, 0xffff0000, v38
	v_lshlrev_b32_e32 v34, 16, v35
	v_and_b32_e32 v35, 0xffff0000, v35
	v_lshlrev_b32_e32 v52, 16, v40
	v_and_b32_e32 v53, 0xffff0000, v40
	v_lshlrev_b32_e32 v40, 16, v41
	v_and_b32_e32 v41, 0xffff0000, v41
	v_pk_add_f32 v[28:29], v[28:29], v[46:47]
	v_pk_add_f32 v[20:21], v[20:21], v[50:51]
	v_lshlrev_b32_e32 v38, 16, v39
	v_and_b32_e32 v39, 0xffff0000, v39
	v_pk_add_f32 v[30:31], v[30:31], v[34:35]
	v_pk_add_f32 v[34:35], v[18:19], v[40:41]
	v_mul_f32_e32 v18, v29, v29
	v_mul_f32_e32 v19, v21, v21
	v_pk_add_f32 v[22:23], v[22:23], v[38:39]
	v_fmac_f32_e32 v18, v28, v28
	v_fmac_f32_e32 v19, v20, v20
	v_lshlrev_b32_e32 v48, 16, v36
	v_and_b32_e32 v49, 0xffff0000, v36
	v_lshlrev_b32_e32 v36, 16, v37
	v_and_b32_e32 v37, 0xffff0000, v37
	v_fmac_f32_e32 v18, v30, v30
	v_fmac_f32_e32 v19, v22, v22
	v_pk_add_f32 v[26:27], v[26:27], v[36:37]
	v_pk_add_f32 v[24:25], v[24:25], v[48:49]
	v_pk_add_f32 v[36:37], v[16:17], v[52:53]
	v_fmac_f32_e32 v18, v31, v31
	v_fmac_f32_e32 v19, v23, v23
	v_fmac_f32_e32 v18, v24, v24
	v_fmac_f32_e32 v19, v36, v36
	v_fmac_f32_e32 v18, v25, v25
	v_fmac_f32_e32 v19, v37, v37
	v_fmac_f32_e32 v18, v26, v26
	v_fmac_f32_e32 v19, v34, v34
	v_fmac_f32_e32 v18, v27, v27
	v_fmac_f32_e32 v19, v35, v35
	v_cvt_pk_bf16_f32 v16, v28, v29
	v_add_f32_e32 v28, v18, v19
	ds_bpermute_b32 v29, v211, v28
	v_cvt_pk_bf16_f32 v17, v30, v31
	v_cvt_pk_bf16_f32 v18, v24, v25
	v_cvt_pk_bf16_f32 v19, v26, v27
	global_store_dwordx4 v[42:43], v[16:19], off
	s_waitcnt lgkmcnt(0)
	s_nop 0
	v_add_f32_e32 v16, v28, v29
	ds_bpermute_b32 v17, v212, v16
	v_cvt_pk_bf16_f32 v18, v20, v21
	v_cvt_pk_bf16_f32 v19, v22, v23
	v_cvt_pk_bf16_f32 v20, v36, v37
	v_cvt_pk_bf16_f32 v21, v34, v35
	global_store_dwordx4 v[44:45], v[18:21], off offset:256
	s_and_saveexec_b64 s[10:11], s[6:7]
	s_cbranch_execz .LBB0_812
	s_waitcnt lgkmcnt(0)
	v_add_f32_e32 v16, v16, v17
	ds_add_f32 v154, v16 offset:640
.LBB0_812:
	s_or_b64 exec, exec, s[10:11]
	v_add_co_u32_e32 v24, vcc, 0xb0000, v32
	v_lshl_add_u64 v[26:27], v[32:33], 0, s[24:25]
	s_nop 0
	v_addc_co_u32_e32 v25, vcc, 0, v33, vcc
	s_waitcnt lgkmcnt(0)
	s_waitcnt vmcnt(14)
	v_mov_b32_e32 v16, v242
	v_mov_b32_e32 v17, v243
	v_mov_b32_e32 v18, v244
	v_mov_b32_e32 v19, v245
	v_mov_b32_e32 v20, v248
	v_mov_b32_e32 v21, v249
	v_mov_b32_e32 v22, v250
	v_mov_b32_e32 v23, v251
	v_lshlrev_b32_e32 v28, 16, v16
	v_and_b32_e32 v29, 0xffff0000, v16
	v_lshlrev_b32_e32 v32, 16, v20
	v_and_b32_e32 v33, 0xffff0000, v20
	v_lshlrev_b32_e32 v16, 16, v17
	v_and_b32_e32 v17, 0xffff0000, v17
	v_lshlrev_b32_e32 v34, 16, v22
	v_and_b32_e32 v35, 0xffff0000, v22
	v_lshlrev_b32_e32 v22, 16, v23
	v_and_b32_e32 v23, 0xffff0000, v23
	v_pk_add_f32 v[12:13], v[12:13], v[28:29]
	v_pk_add_f32 v[4:5], v[4:5], v[32:33]
	v_lshlrev_b32_e32 v20, 16, v21
	v_and_b32_e32 v21, 0xffff0000, v21
	v_pk_add_f32 v[14:15], v[14:15], v[16:17]
	v_pk_add_f32 v[16:17], v[2:3], v[22:23]
	v_mul_f32_e32 v2, v13, v13
	v_mul_f32_e32 v3, v5, v5
	v_pk_add_f32 v[6:7], v[6:7], v[20:21]
	v_fmac_f32_e32 v2, v12, v12
	v_fmac_f32_e32 v3, v4, v4
	v_lshlrev_b32_e32 v30, 16, v18
	v_and_b32_e32 v31, 0xffff0000, v18
	v_lshlrev_b32_e32 v18, 16, v19
	v_and_b32_e32 v19, 0xffff0000, v19
	v_fmac_f32_e32 v2, v14, v14
	v_fmac_f32_e32 v3, v6, v6
	v_pk_add_f32 v[10:11], v[10:11], v[18:19]
	v_pk_add_f32 v[8:9], v[8:9], v[30:31]
	v_pk_add_f32 v[18:19], v[0:1], v[34:35]
	v_fmac_f32_e32 v2, v15, v15
	v_fmac_f32_e32 v3, v7, v7
	v_fmac_f32_e32 v2, v8, v8
	v_fmac_f32_e32 v3, v18, v18
	v_fmac_f32_e32 v2, v9, v9
	v_fmac_f32_e32 v3, v19, v19
	v_fmac_f32_e32 v2, v10, v10
	v_fmac_f32_e32 v3, v16, v16
	v_fmac_f32_e32 v2, v11, v11
	v_fmac_f32_e32 v3, v17, v17
	v_cvt_pk_bf16_f32 v0, v12, v13
	v_add_f32_e32 v12, v2, v3
	ds_bpermute_b32 v13, v211, v12
	v_cvt_pk_bf16_f32 v1, v14, v15
	v_cvt_pk_bf16_f32 v2, v8, v9
	v_cvt_pk_bf16_f32 v3, v10, v11
	global_store_dwordx4 v[24:25], v[0:3], off
	s_waitcnt lgkmcnt(0)
	s_nop 0
	v_add_f32_e32 v0, v12, v13
	ds_bpermute_b32 v1, v212, v0
	v_cvt_pk_bf16_f32 v2, v4, v5
	v_cvt_pk_bf16_f32 v3, v6, v7
	v_cvt_pk_bf16_f32 v4, v18, v19
	v_cvt_pk_bf16_f32 v5, v16, v17
	global_store_dwordx4 v[26:27], v[2:5], off offset:256
	s_and_saveexec_b64 s[10:11], s[6:7]
	s_cbranch_execz .LBB0_814
	s_waitcnt lgkmcnt(0)
	v_add_f32_e32 v0, v0, v1
	ds_add_f32 v154, v0 offset:704

.LBB0_978:
	v_lshl_add_u32 v148, s45, 8, v150
	v_lshl_or_b32 v146, s46, 8, v152
	v_lshl_add_u32 v144, v148, 11, v146
	v_lshlrev_b32_e32 v145, 1, v144
	v_lshlrev_b32_e32 v147, 2, v144
	s_and_b64 vcc, exec, s[0:1]
	s_mov_b64 s[0:1], -1
	global_load_dwordx4 v[156:159], v145, s[66:67] nt
	global_load_dwordx4 v[160:163], v145, s[66:67] offset:256 nt
	v_add_u32_e32 v149, 0x10000, v145
	global_load_dwordx4 v[164:167], v149, s[66:67] nt
	global_load_dwordx4 v[168:171], v149, s[66:67] offset:256 nt
	v_add_u32_e32 v149, 0x20000, v145
	global_load_dwordx4 v[172:175], v149, s[66:67] nt
	global_load_dwordx4 v[176:179], v149, s[66:67] offset:256 nt
	v_add_u32_e32 v149, 0x30000, v145
	global_load_dwordx4 v[180:183], v149, s[66:67] nt
	global_load_dwordx4 v[184:187], v149, s[66:67] offset:256 nt
	v_add_u32_e32 v149, 0x80000, v145
	global_load_dwordx4 v[188:191], v149, s[66:67] nt
	global_load_dwordx4 v[192:195], v149, s[66:67] offset:256 nt
	v_add_u32_e32 v149, 0x90000, v145
	global_load_dwordx4 v[196:199], v149, s[66:67] nt
	global_load_dwordx4 v[200:203], v149, s[66:67] offset:256 nt
	v_add_u32_e32 v149, 0xa0000, v145
	global_load_dwordx4 v[204:207], v149, s[66:67] nt
	global_load_dwordx4 v[208:211], v149, s[66:67] offset:256 nt
	v_add_u32_e32 v149, 0xb0000, v145
	global_load_dwordx4 v[212:215], v149, s[66:67] nt
	global_load_dwordx4 v[216:219], v149, s[66:67] offset:256 nt
	s_waitcnt vmcnt(14)
	v_lshlrev_b32_e32 v224, 16, v156
	v_and_b32_e32 v225, 0xffff0000, v156
	v_lshlrev_b32_e32 v226, 16, v157
	v_and_b32_e32 v227, 0xffff0000, v157
	v_lshlrev_b32_e32 v228, 16, v158
	v_and_b32_e32 v229, 0xffff0000, v158
	v_lshlrev_b32_e32 v230, 16, v159
	v_and_b32_e32 v231, 0xffff0000, v159
	v_pk_add_f32 v[124:125], v[124:125], v[224:225]
	v_pk_add_f32 v[126:127], v[126:127], v[226:227]
	v_pk_add_f32 v[120:121], v[120:121], v[228:229]
	v_pk_add_f32 v[122:123], v[122:123], v[230:231]
	global_store_dwordx4 v147, v[124:127], s[88:89] nt
	global_store_dwordx4 v147, v[120:123], s[88:89] offset:16 nt
	v_lshlrev_b32_e32 v224, 16, v160
	v_and_b32_e32 v225, 0xffff0000, v160
	v_lshlrev_b32_e32 v226, 16, v161
	v_and_b32_e32 v227, 0xffff0000, v161
	v_lshlrev_b32_e32 v228, 16, v162
	v_and_b32_e32 v229, 0xffff0000, v162
	v_lshlrev_b32_e32 v230, 16, v163
	v_and_b32_e32 v231, 0xffff0000, v163
	v_pk_add_f32 v[116:117], v[116:117], v[224:225]
	v_pk_add_f32 v[118:119], v[118:119], v[226:227]
	v_pk_add_f32 v[112:113], v[112:113], v[228:229]
	v_pk_add_f32 v[114:115], v[114:115], v[230:231]
	global_store_dwordx4 v147, v[116:119], s[88:89] offset:512 nt
	global_store_dwordx4 v147, v[112:115], s[88:89] offset:528 nt
	s_waitcnt vmcnt(16)
	v_add_u32_e32 v149, 0x20000, v147
	v_lshlrev_b32_e32 v224, 16, v164
	v_and_b32_e32 v225, 0xffff0000, v164
	v_lshlrev_b32_e32 v226, 16, v165
	v_and_b32_e32 v227, 0xffff0000, v165
	v_lshlrev_b32_e32 v228, 16, v166
	v_and_b32_e32 v229, 0xffff0000, v166
	v_lshlrev_b32_e32 v230, 16, v167
	v_and_b32_e32 v231, 0xffff0000, v167
	v_pk_add_f32 v[108:109], v[108:109], v[224:225]
	v_pk_add_f32 v[110:111], v[110:111], v[226:227]
	v_pk_add_f32 v[104:105], v[104:105], v[228:229]
	v_pk_add_f32 v[106:107], v[106:107], v[230:231]
	global_store_dwordx4 v149, v[108:111], s[88:89] nt
	global_store_dwordx4 v149, v[104:107], s[88:89] offset:16 nt
	v_lshlrev_b32_e32 v224, 16, v168
	v_and_b32_e32 v225, 0xffff0000, v168
	v_lshlrev_b32_e32 v226, 16, v169
	v_and_b32_e32 v227, 0xffff0000, v169
	v_lshlrev_b32_e32 v228, 16, v170
	v_and_b32_e32 v229, 0xffff0000, v170
	v_lshlrev_b32_e32 v230, 16, v171
	v_and_b32_e32 v231, 0xffff0000, v171
	v_pk_add_f32 v[100:101], v[100:101], v[224:225]
	v_pk_add_f32 v[102:103], v[102:103], v[226:227]
	v_pk_add_f32 v[96:97], v[96:97], v[228:229]
	v_pk_add_f32 v[98:99], v[98:99], v[230:231]
	global_store_dwordx4 v149, v[100:103], s[88:89] offset:512 nt
	global_store_dwordx4 v149, v[96:99], s[88:89] offset:528 nt
	s_waitcnt vmcnt(18)
	v_add_u32_e32 v149, 0x40000, v147
	v_lshlrev_b32_e32 v224, 16, v172
	v_and_b32_e32 v225, 0xffff0000, v172
	v_lshlrev_b32_e32 v226, 16, v173
	v_and_b32_e32 v227, 0xffff0000, v173
	v_lshlrev_b32_e32 v228, 16, v174
	v_and_b32_e32 v229, 0xffff0000, v174
	v_lshlrev_b32_e32 v230, 16, v175
	v_and_b32_e32 v231, 0xffff0000, v175
	v_pk_add_f32 v[92:93], v[92:93], v[224:225]
	v_pk_add_f32 v[94:95], v[94:95], v[226:227]
	v_pk_add_f32 v[88:89], v[88:89], v[228:229]
	v_pk_add_f32 v[90:91], v[90:91], v[230:231]
	global_store_dwordx4 v149, v[92:95], s[88:89] nt
	global_store_dwordx4 v149, v[88:91], s[88:89] offset:16 nt
	v_lshlrev_b32_e32 v224, 16, v176
	v_and_b32_e32 v225, 0xffff0000, v176
	v_lshlrev_b32_e32 v226, 16, v177
	v_and_b32_e32 v227, 0xffff0000, v177
	v_lshlrev_b32_e32 v228, 16, v178
	v_and_b32_e32 v229, 0xffff0000, v178
	v_lshlrev_b32_e32 v230, 16, v179
	v_and_b32_e32 v231, 0xffff0000, v179
	v_pk_add_f32 v[84:85], v[84:85], v[224:225]
	v_pk_add_f32 v[86:87], v[86:87], v[226:227]
	v_pk_add_f32 v[80:81], v[80:81], v[228:229]
	v_pk_add_f32 v[82:83], v[82:83], v[230:231]
	global_store_dwordx4 v149, v[84:87], s[88:89] offset:512 nt
	global_store_dwordx4 v149, v[80:83], s[88:89] offset:528 nt
	s_waitcnt vmcnt(20)
	v_add_u32_e32 v149, 0x60000, v147
	v_lshlrev_b32_e32 v224, 16, v180
	v_and_b32_e32 v225, 0xffff0000, v180
	v_lshlrev_b32_e32 v226, 16, v181
	v_and_b32_e32 v227, 0xffff0000, v181
	v_lshlrev_b32_e32 v228, 16, v182
	v_and_b32_e32 v229, 0xffff0000, v182
	v_lshlrev_b32_e32 v230, 16, v183
	v_and_b32_e32 v231, 0xffff0000, v183
	v_pk_add_f32 v[76:77], v[76:77], v[224:225]
	v_pk_add_f32 v[78:79], v[78:79], v[226:227]
	v_pk_add_f32 v[72:73], v[72:73], v[228:229]
	v_pk_add_f32 v[74:75], v[74:75], v[230:231]
	global_store_dwordx4 v149, v[76:79], s[88:89] nt
	global_store_dwordx4 v149, v[72:75], s[88:89] offset:16 nt
	v_lshlrev_b32_e32 v224, 16, v184
	v_and_b32_e32 v225, 0xffff0000, v184
	v_lshlrev_b32_e32 v226, 16, v185
	v_and_b32_e32 v227, 0xffff0000, v185
	v_lshlrev_b32_e32 v228, 16, v186
	v_and_b32_e32 v229, 0xffff0000, v186
	v_lshlrev_b32_e32 v230, 16, v187
	v_and_b32_e32 v231, 0xffff0000, v187
	v_pk_add_f32 v[68:69], v[68:69], v[224:225]
	v_pk_add_f32 v[70:71], v[70:71], v[226:227]
	v_pk_add_f32 v[64:65], v[64:65], v[228:229]
	v_pk_add_f32 v[66:67], v[66:67], v[230:231]
	global_store_dwordx4 v149, v[68:71], s[88:89] offset:512 nt
	global_store_dwordx4 v149, v[64:67], s[88:89] offset:528 nt
	s_waitcnt vmcnt(22)
	v_add_u32_e32 v149, 0x100000, v147
	v_lshlrev_b32_e32 v224, 16, v188
	v_and_b32_e32 v225, 0xffff0000, v188
	v_lshlrev_b32_e32 v226, 16, v189
	v_and_b32_e32 v227, 0xffff0000, v189
	v_lshlrev_b32_e32 v228, 16, v190
	v_and_b32_e32 v229, 0xffff0000, v190
	v_lshlrev_b32_e32 v230, 16, v191
	v_and_b32_e32 v231, 0xffff0000, v191
	v_pk_add_f32 v[60:61], v[60:61], v[224:225]
	v_pk_add_f32 v[62:63], v[62:63], v[226:227]
	v_pk_add_f32 v[56:57], v[56:57], v[228:229]
	v_pk_add_f32 v[58:59], v[58:59], v[230:231]
	global_store_dwordx4 v149, v[60:63], s[88:89] nt
	global_store_dwordx4 v149, v[56:59], s[88:89] offset:16 nt
	v_lshlrev_b32_e32 v224, 16, v192
	v_and_b32_e32 v225, 0xffff0000, v192
	v_lshlrev_b32_e32 v226, 16, v193
	v_and_b32_e32 v227, 0xffff0000, v193
	v_lshlrev_b32_e32 v228, 16, v194
	v_and_b32_e32 v229, 0xffff0000, v194
	v_lshlrev_b32_e32 v230, 16, v195
	v_and_b32_e32 v231, 0xffff0000, v195
	v_pk_add_f32 v[52:53], v[52:53], v[224:225]
	v_pk_add_f32 v[54:55], v[54:55], v[226:227]
	v_pk_add_f32 v[48:49], v[48:49], v[228:229]
	v_pk_add_f32 v[50:51], v[50:51], v[230:231]
	global_store_dwordx4 v149, v[52:55], s[88:89] offset:512 nt
	global_store_dwordx4 v149, v[48:51], s[88:89] offset:528 nt
	s_waitcnt vmcnt(24)
	v_add_u32_e32 v149, 0x120000, v147
	v_lshlrev_b32_e32 v224, 16, v196
	v_and_b32_e32 v225, 0xffff0000, v196
	v_lshlrev_b32_e32 v226, 16, v197
	v_and_b32_e32 v227, 0xffff0000, v197
	v_lshlrev_b32_e32 v228, 16, v198
	v_and_b32_e32 v229, 0xffff0000, v198
	v_lshlrev_b32_e32 v230, 16, v199
	v_and_b32_e32 v231, 0xffff0000, v199
	v_pk_add_f32 v[44:45], v[44:45], v[224:225]
	v_pk_add_f32 v[46:47], v[46:47], v[226:227]
	v_pk_add_f32 v[40:41], v[40:41], v[228:229]
	v_pk_add_f32 v[42:43], v[42:43], v[230:231]
	global_store_dwordx4 v149, v[44:47], s[88:89] nt
	global_store_dwordx4 v149, v[40:43], s[88:89] offset:16 nt
	v_lshlrev_b32_e32 v224, 16, v200
	v_and_b32_e32 v225, 0xffff0000, v200
	v_lshlrev_b32_e32 v226, 16, v201
	v_and_b32_e32 v227, 0xffff0000, v201
	v_lshlrev_b32_e32 v228, 16, v202
	v_and_b32_e32 v229, 0xffff0000, v202
	v_lshlrev_b32_e32 v230, 16, v203
	v_and_b32_e32 v231, 0xffff0000, v203
	v_pk_add_f32 v[36:37], v[36:37], v[224:225]
	v_pk_add_f32 v[38:39], v[38:39], v[226:227]
	v_pk_add_f32 v[32:33], v[32:33], v[228:229]
	v_pk_add_f32 v[34:35], v[34:35], v[230:231]
	global_store_dwordx4 v149, v[36:39], s[88:89] offset:512 nt
	global_store_dwordx4 v149, v[32:35], s[88:89] offset:528 nt
	s_waitcnt vmcnt(26)
	v_add_u32_e32 v149, 0x140000, v147
	v_lshlrev_b32_e32 v224, 16, v204
	v_and_b32_e32 v225, 0xffff0000, v204
	v_lshlrev_b32_e32 v226, 16, v205
	v_and_b32_e32 v227, 0xffff0000, v205
	v_lshlrev_b32_e32 v228, 16, v206
	v_and_b32_e32 v229, 0xffff0000, v206
	v_lshlrev_b32_e32 v230, 16, v207
	v_and_b32_e32 v231, 0xffff0000, v207
	v_pk_add_f32 v[28:29], v[28:29], v[224:225]
	v_pk_add_f32 v[30:31], v[30:31], v[226:227]
	v_pk_add_f32 v[24:25], v[24:25], v[228:229]
	v_pk_add_f32 v[26:27], v[26:27], v[230:231]
	global_store_dwordx4 v149, v[28:31], s[88:89] nt
	global_store_dwordx4 v149, v[24:27], s[88:89] offset:16 nt
	v_lshlrev_b32_e32 v224, 16, v208
	v_and_b32_e32 v225, 0xffff0000, v208
	v_lshlrev_b32_e32 v226, 16, v209
	v_and_b32_e32 v227, 0xffff0000, v209
	v_lshlrev_b32_e32 v228, 16, v210
	v_and_b32_e32 v229, 0xffff0000, v210
	v_lshlrev_b32_e32 v230, 16, v211
	v_and_b32_e32 v231, 0xffff0000, v211
	v_pk_add_f32 v[20:21], v[20:21], v[224:225]
	v_pk_add_f32 v[22:23], v[22:23], v[226:227]
	v_pk_add_f32 v[16:17], v[16:17], v[228:229]
	v_pk_add_f32 v[18:19], v[18:19], v[230:231]
	global_store_dwordx4 v149, v[20:23], s[88:89] offset:512 nt
	global_store_dwordx4 v149, v[16:19], s[88:89] offset:528 nt
	s_waitcnt vmcnt(28)
	v_add_u32_e32 v149, 0x160000, v147
	v_lshlrev_b32_e32 v224, 16, v212
	v_and_b32_e32 v225, 0xffff0000, v212
	v_lshlrev_b32_e32 v226, 16, v213
	v_and_b32_e32 v227, 0xffff0000, v213
	v_lshlrev_b32_e32 v228, 16, v214
	v_and_b32_e32 v229, 0xffff0000, v214
	v_lshlrev_b32_e32 v230, 16, v215
	v_and_b32_e32 v231, 0xffff0000, v215
	v_pk_add_f32 v[12:13], v[12:13], v[224:225]
	v_pk_add_f32 v[14:15], v[14:15], v[226:227]
	v_pk_add_f32 v[8:9], v[8:9], v[228:229]
	v_pk_add_f32 v[10:11], v[10:11], v[230:231]
	global_store_dwordx4 v149, v[12:15], s[88:89] nt
	global_store_dwordx4 v149, v[8:11], s[88:89] offset:16 nt
	v_lshlrev_b32_e32 v224, 16, v216
	v_and_b32_e32 v225, 0xffff0000, v216
	v_lshlrev_b32_e32 v226, 16, v217
	v_and_b32_e32 v227, 0xffff0000, v217
	v_lshlrev_b32_e32 v228, 16, v218
	v_and_b32_e32 v229, 0xffff0000, v218
	v_lshlrev_b32_e32 v230, 16, v219
	v_and_b32_e32 v231, 0xffff0000, v219
	v_pk_add_f32 v[4:5], v[4:5], v[224:225]
	v_pk_add_f32 v[6:7], v[6:7], v[226:227]
	v_pk_add_f32 v[0:1], v[0:1], v[228:229]
	v_pk_add_f32 v[2:3], v[2:3], v[230:231]
	global_store_dwordx4 v149, v[4:7], s[88:89] offset:512 nt
	global_store_dwordx4 v149, v[0:3], s[88:89] offset:528 nt
	s_cbranch_vccnz .LBB0_963
	s_andn2_b64 vcc, exec, s[4:5]
	s_cbranch_vccnz .LBB0_962
	s_barrier
	s_branch .LBB0_962
